# grid barrier: issue the acquire buffer_inv before the release spin instead of after
# speedup vs baseline: 1.0102x; 1.0081x over previous
.LBB0_879:
	s_or_b64 exec, exec, s[4:5]
	v_cvt_f32_u32_e32 v4, v2
	s_waitcnt vmcnt(0)
	v_readfirstlane_b32 s4, v3
	v_sub_u32_e32 v3, 0, v2
	v_rcp_iflag_f32_e32 v4, v4
	v_add_u32_e32 v5, s4, v1
	v_mul_f32_e32 v4, 0x4f7ffffe, v4
	v_cvt_u32_f32_e32 v4, v4
	v_mul_lo_u32 v1, v3, v4
	v_mul_hi_u32 v1, v4, v1
	v_add_u32_e32 v1, v4, v1
	v_mul_hi_u32 v1, v5, v1
	v_mul_lo_u32 v3, v1, v2
	v_sub_u32_e32 v3, v5, v3
	v_add_u32_e32 v4, 1, v1
	v_cmp_ge_u32_e32 vcc, v3, v2
	s_nop 1
	v_cndmask_b32_e32 v1, v1, v4, vcc
	v_sub_u32_e32 v4, v3, v2
	v_cndmask_b32_e32 v3, v3, v4, vcc
	v_add_u32_e32 v4, 1, v1
	v_cmp_ge_u32_e32 vcc, v3, v2
	v_add_u32_e32 v3, 1, v5
	s_nop 0
	v_cndmask_b32_e32 v1, v1, v4, vcc
	v_mul_lo_u32 v4, v2, v1
	v_add_u32_e32 v2, v4, v2
	v_cmp_ne_u32_e32 vcc, v3, v2
	s_and_saveexec_b64 s[4:5], vcc
	s_xor_b64 s[4:5], exec, s[4:5]
	s_cbranch_execz .LBB0_893
	v_readlane_b32 s12, v254, 10
	v_readlane_b32 s13, v254, 11
	s_waitcnt lgkmcnt(0)
	buffer_inv sc1
	s_nop 3
	global_load_dword v0, v145, s[12:13] sc1
	s_waitcnt vmcnt(0)
	v_cmp_eq_u32_e32 vcc, v0, v1
	s_and_saveexec_b64 s[12:13], vcc
	s_cbranch_execz .LBB0_892
	s_mov_b32 s15, 1
	s_mov_b64 s[16:17], 0
	s_branch .LBB0_883

.LBB0_892:
	s_or_b64 exec, exec, s[12:13]
	s_waitcnt vmcnt(0)
	s_waitcnt vmcnt(0)

.LBB0_896:
	s_or_b64 exec, exec, s[12:13]
	buffer_inv sc1
	s_waitcnt vmcnt(0)
	v_readfirstlane_b32 s4, v2
	v_cvt_f32_u32_e32 v2, v0
	v_sub_u32_e32 v3, 0, v0
	v_add_u32_e32 v1, s4, v1
	v_readlane_b32 s4, v254, 14
	v_rcp_iflag_f32_e32 v2, v2
	v_readlane_b32 s5, v254, 15
	s_mov_b64 s[12:13], -1
	v_mul_f32_e32 v2, 0x4f7ffffe, v2
	v_cvt_u32_f32_e32 v2, v2
	v_mul_lo_u32 v3, v3, v2
	v_mul_hi_u32 v3, v2, v3
	v_add_u32_e32 v2, v2, v3
	v_mul_hi_u32 v2, v1, v2
	v_mul_lo_u32 v3, v2, v0
	v_sub_u32_e32 v3, v1, v3
	v_cmp_ge_u32_e32 vcc, v3, v0
	v_add_u32_e32 v4, 1, v2
	v_add_u32_e32 v1, 1, v1
	v_cndmask_b32_e32 v2, v2, v4, vcc
	v_sub_u32_e32 v4, v3, v0
	v_cndmask_b32_e32 v3, v3, v4, vcc
	v_cmp_ge_u32_e32 vcc, v3, v0
	v_add_u32_e32 v3, 1, v2
	s_nop 0
	v_cndmask_b32_e32 v2, v2, v3, vcc
	v_mul_lo_u32 v3, v0, v2
	v_add_u32_e32 v0, v3, v0
	v_cmp_ne_u32_e32 vcc, v1, v0
	v_mov_b64_e32 v[0:1], s[4:5]
	s_and_saveexec_b64 s[4:5], vcc
	s_cbranch_execz .LBB0_908
	v_readlane_b32 s12, v254, 14
	v_readlane_b32 s13, v254, 15
	s_mov_b64 s[16:17], 0
	s_nop 3
	global_load_dword v0, v145, s[12:13] sc1
	s_waitcnt vmcnt(0)
	v_cmp_eq_u32_e32 vcc, v0, v2
	s_and_saveexec_b64 s[12:13], vcc
	s_cbranch_execz .LBB0_907
	s_mov_b32 s15, 1
	s_branch .LBB0_900

.LBB0_910:
	s_or_b64 exec, exec, s[4:5]
	s_mov_b64 s[4:5], exec
	v_mbcnt_lo_u32_b32 v0, s4, 0
	v_mbcnt_hi_u32_b32 v0, s5, v0
	v_cmp_eq_u32_e32 vcc, 0, v0
	s_waitcnt vmcnt(0)
	s_and_saveexec_b64 s[12:13], vcc
	s_cbranch_execz .LBB0_912
	s_bcnt1_i32_b64 s4, s[4:5]
	v_mov_b32_e32 v0, s4
	v_readlane_b32 s4, v254, 10
	v_readlane_b32 s5, v254, 11
	s_nop 4
	global_atomic_add v145, v0, s[4:5]
